# P3+P5: CUs enter the phase in 4 groups 4us apart (by blockIdx bits 3-4) so EpiRes bursts spread out
# speedup vs baseline: 1.0047x; 1.0047x over previous
; #define PG8_BAR __builtin_amdgcn_s_barrier()
; template <class Epi, bool HALO>
; __device__ __forceinline__ void gemm_phase(LAS unsigned char* lds, const bf16_t* Ag, const bf16_t* Btg, const int K, const int nM, const int nN, const int G, const int cidx, const int wave_, const Epi& E) {
;     int tid_ = fresh_tid(wave_); asm volatile("" : "+v"(tid_));
;     const int tid = tid_, wid = __builtin_amdgcn_readfirstlane(tid >> 6), lane = tid & 63, wr = wid >> 2, wc = wid & 3, fr = lane & 15, fq = lane >> 4;
;     const int nt = K / BK;
;     StaticOrder S; S.init(nM, nN, G, cidx);
;     unsigned voffA[2], voffB[2];
; #pragma unroll
;     for (int i = 0; i < 2; ++i) { int R, C; stage_rc(tid * 16 + i * 8192, R, C); const int Rb = (R & ~31) + perm32(R & 31);
;         const int Ra = HALO ? (R - 2 * (R >> 6)) : R;
;         voffA[i] = (unsigned)(Ra * K + C) * 2u; voffB[i] = (unsigned)(Rb * K + C) * 2u; }
;     const size_t kstep = (size_t)(BK * 2);
;     const size_t hstepB = (size_t)HALF * K * 2;
;     const size_t hstepA = HALO ? (size_t)124 * K * 2 : hstepB;
;     const unsigned ldsw = (unsigned)wid * 1024u;
;     const int aoff = lds_byte(wr * 64 + fr, fq * 8), boff = lds_byte(wc * 32 + fr, fq * 8);
;     ...
;     auto halo_row0 = [](int pm) -> long { int sb, t0, sl; halo_decode(pm, sb, t0, sl); return (long)sb + t0 - 1; };
;     Unit cur, nxt; int ui = 0;
;     if (!S.next(0, cur)) return;
;     f32x4 acc[2][2][4][2];
; #pragma unroll
;     for (int a = 0; a < 2; ++a)
; #pragma unroll
;         for (int b = 0; b < 2; ++b)
; #pragma unroll
;             for (int m = 0; m < 4; ++m)
; #pragma unroll
;                 for (int n = 0; n < 2; ++n) acc[a][b][m][n] = (f32x4){0.f, 0.f, 0.f, 0.f};
;     bf16x8 At[4][2], B0[2][2], B1[2][2];
;     const char* cA = PG8_ABASE(cur.pm); const char* cB = PG8_BBASE(cur.pn);
;     PG8_STAGE(PG8_SB(0, 0), cB, voffB); PG8_STAGE(PG8_SB(0, 1), cB + hstepB, voffB); PG8_STAGE(PG8_SA(0, 0), cA, voffA); PG8_STAGE(PG8_SA(0, 1), cA + hstepA, voffA);
;     if (wr == 1) PG8_BAR;
;     PG8_WAIT_V(2); PG8_BAR;
; __global__ void __launch_bounds__(NTHREADS, 2) hymba_fwd(Args args) {
;     ...
;         {
;             PHASE_ENV unsigned char* wl = ws + l * WS_WL;
;             pg8::EpiRes E{nullptr, nullptr, XN, nullptr, PS};
;             pg8::gemm_phase<pg8::EpiRes, false>(ldsl, MIX, (const bf16_t*)(wl + WO_OUT), DM, MT / 256, DM / 256, G, bx, wave, E);
.LBB0_688:
	s_or_b64 exec, exec, s[2:3]
	v_readlane_b32 s2, v254, 0
	v_readlane_b32 s3, v254, 1
	s_waitcnt lgkmcnt(0)
	v_mov_b32_e32 v0, v145
	s_barrier
	v_readlane_b32 s98, v254, 58
	s_lshr_b32 s98, s98, 3
	s_and_b32 s98, s98, 3
	s_mul_i32 s101, s98, 400
	s_cmp_eq_u32 s101, 0
	s_cbranch_scc1 STG3_skip
	s_memrealtime s[98:99]
	s_waitcnt lgkmcnt(0)
	s_mov_b32 s100, s98
STG3_spin:
	s_sleep 2
	s_memrealtime s[98:99]
	s_waitcnt lgkmcnt(0)
	s_sub_u32 s98, s98, s100
	s_cmp_lt_u32 s98, s101
	s_cbranch_scc1 STG3_spin
STG3_skip:
	v_readlane_b32 s0, v254, 14
	v_mbcnt_lo_u32_b32 v0, -1, v0
	v_mbcnt_hi_u32_b32 v0, -1, v0
	v_readlane_b32 s1, v254, 15
	v_add_u32_e32 v14, s81, v0
	s_andn2_b64 vcc, exec, s[0:1]
	v_cndmask_b32_e64 v0, 0, 1, s[0:1]
	v_cmp_ne_u32_e64 s[16:17], 1, v0
	v_readfirstlane_b32 s4, v14
	s_cbranch_vccnz .LBB0_720
	v_lshlrev_b32_e32 v0, 4, v14
	v_add_u32_e32 v1, 0x2000, v0
	v_ashrrev_i32_e32 v2, 31, v1
	v_lshrrev_b32_e32 v2, 22, v2
	v_add_u32_e32 v2, v1, v2
	v_ashrrev_i32_e32 v8, 10, v2
	v_mul_i32_i24_e32 v2, 0x400, v8
	v_sub_u32_e32 v1, v1, v2
	v_lshrrev_b32_e32 v2, 4, v1
	v_bitop3_b32 v1, v2, v1, 32 bitop3:0x6c
	v_ashrrev_i32_e32 v2, 31, v1
	v_lshrrev_b32_e32 v2, 26, v2
	v_add_u32_e32 v2, v1, v2
	v_lshlrev_b32_e32 v3, 3, v8
	v_ashrrev_i32_e32 v9, 6, v2
	v_and_b32_e32 v3, -16, v3
	v_add_u32_e32 v3, v9, v3
	v_and_b32_e32 v4, 3, v9
	s_mov_b32 s7, 0x1fffe0
	v_lshrrev_b32_e32 v5, 2, v3
	v_lshlrev_b32_e32 v6, 1, v3
	v_and_b32_e32 v2, 0xc0, v2
	v_and_or_b32 v4, v3, s7, v4
	v_and_b32_e32 v5, 4, v5
	v_and_b32_e32 v6, 24, v6
	v_sub_u32_e32 v1, v1, v2
	v_or3_b32 v4, v4, v5, v6
	v_lshlrev_b32_e32 v5, 5, v8
	v_ashrrev_i16_sdwa v1, v184, sext(v1) dst_sel:DWORD dst_unused:UNUSED_PAD src0_sel:DWORD src1_sel:BYTE_0
	v_and_b32_e32 v5, 32, v5
	v_bfe_i32 v10, v1, 0, 16
	v_add_lshl_u32 v1, v5, v10, 1
	v_lshl_add_u32 v128, v4, 11, v1
	v_lshl_add_u32 v130, v3, 11, v1
	v_bfe_i32 v1, v14, 27, 1
	v_lshrrev_b32_e32 v1, 22, v1
	v_add_u32_e32 v1, v0, v1
	s_load_dwordx2 s[2:3], s[2:3], 0xe0
	v_and_b32_e32 v1, 0xfffffc00, v1
	v_sub_u32_e32 v0, v0, v1
	v_lshrrev_b32_e32 v1, 4, v0
	v_ashrrev_i32_e32 v2, 31, v14
	v_bitop3_b32 v0, v1, v0, 32 bitop3:0x6c
	v_lshrrev_b32_e32 v2, 26, v2
	v_ashrrev_i32_e32 v1, 31, v0
	v_add_u32_e32 v2, v14, v2
	s_waitcnt lgkmcnt(0)
	s_add_u32 s0, s2, 0x28400000
	v_lshrrev_b32_e32 v1, 26, v1
	v_ashrrev_i32_e32 v12, 6, v2
	s_addc_u32 s1, s3, 0
	v_readlane_b32 s5, v255, 6
	v_add_u32_e32 v1, v0, v1
	v_lshlrev_b32_e32 v2, 3, v12
	s_add_u32 s5, s2, s5
	v_ashrrev_i32_e32 v11, 6, v1
	v_and_b32_e32 v2, -16, v2
	s_addc_u32 s6, s3, 0
	v_add_u32_e32 v2, v11, v2
	s_add_u32 s30, s5, 0x500000
	v_and_b32_e32 v3, 3, v11
	v_lshrrev_b32_e32 v4, 2, v2
	v_lshlrev_b32_e32 v5, 1, v2
	v_and_b32_e32 v1, 0xc0, v1
	s_addc_u32 s31, s6, 0
	s_ashr_i32 s6, s4, 6
	v_and_or_b32 v3, v2, s7, v3
	v_and_b32_e32 v4, 4, v4
	v_and_b32_e32 v5, 24, v5
	v_sub_u32_e32 v0, v0, v1
	s_ashr_i32 s5, s4, 8
	s_lshl_b32 s34, s6, 10
	v_or3_b32 v3, v3, v4, v5
	v_lshlrev_b32_e32 v4, 5, v12
	v_ashrrev_i16_sdwa v0, v184, sext(v0) dst_sel:DWORD dst_unused:UNUSED_PAD src0_sel:DWORD src1_sel:BYTE_0
	v_readlane_b32 s8, v254, 26
	v_and_b32_e32 v4, 32, v4
	v_bfe_i32 v13, v0, 0, 16
	v_readlane_b32 s9, v254, 27
	s_add_u32 s26, s30, s8
	v_add_lshl_u32 v0, v4, v13, 1
	s_addc_u32 s27, s31, s9
	s_add_i32 s35, s34, 0
	v_lshl_add_u32 v144, v3, 11, v0
	s_add_i32 m0, s35, 0x10000
	v_lshl_add_u32 v132, v2, 11, v0
	global_load_lds_dwordx4 v144, s[26:27]
	s_add_i32 m0, s35, 0x12000
	s_add_u32 s8, s26, 0x40000
	global_load_lds_dwordx4 v128, s[26:27]
	s_addc_u32 s9, s27, 0
	s_add_i32 m0, s35, 0x14000
	v_mov_b32_e32 v129, v145
	global_load_lds_dwordx4 v144, s[8:9]
	s_add_i32 m0, s35, 0x16000
	v_mov_b32_e32 v133, v145
	global_load_lds_dwordx4 v128, s[8:9]
	v_readlane_b32 s8, v254, 24
	v_readlane_b32 s9, v254, 25
	s_add_u32 s24, s0, s8
	s_addc_u32 s25, s1, s9
	s_add_i32 s36, s35, 0x2000
	s_mov_b32 m0, s35
	s_add_u32 s8, s24, 0x40000
	global_load_lds_dwordx4 v132, s[24:25]
	s_mov_b32 m0, s36
	s_addc_u32 s9, s25, 0
	s_add_i32 s37, s35, 0x4000
	global_load_lds_dwordx4 v130, s[24:25]
	s_mov_b32 m0, s37
	s_add_i32 s38, s35, 0x6000
	global_load_lds_dwordx4 v132, s[8:9]
	s_mov_b32 m0, s38
	v_mov_b32_e32 v131, v145
	global_load_lds_dwordx4 v130, s[8:9]
	s_cmp_eq_u32 s5, 1
	v_lshl_add_u64 v[6:7], s[26:27], 0, v[144:145]
	v_lshl_add_u64 v[4:5], s[26:27], 0, v[128:129]
	v_lshl_add_u64 v[0:1], s[24:25], 0, v[132:133]
	s_cselect_b64 s[8:9], -1, 0
	s_cmp_lg_u32 s5, 1
	v_lshl_add_u64 v[2:3], s[24:25], 0, v[130:131]
	s_cbranch_scc1 .LBB0_691
	s_barrier

; #define GRID_BAR() do { CArgsP apb_ = (CArgsP)__builtin_amdgcn_kernarg_segment_ptr(); asm volatile("" : "+s"(apb_)); XcdBarrier b_; b_.bar = (unsigned*)(apb_->ws + WS_BAR); b_.x = xb_xcc_id(); \
;         b_.st = (volatile LAS unsigned*)((LAS unsigned char*)lds + OFF_BARST); xcd_barrier(b_, fresh_tid(wave) == 0); } while (0)
; __global__ void __launch_bounds__(NTHREADS, 2) hymba_fwd(Args args) {
;     ...
;         GRID_BAR();
;         {
;             PHASE_ENV unsigned char* wl = ws + l * WS_WL;
;             pg8::EpiRes E{nullptr, nullptr, XN, l == 1 ? out : nullptr, l == 0 ? PS : nullptr};
;             pg8::gemm_phase<pg8::EpiRes, false>(ldsl, GB, (const bf16_t*)(wl + WO_DN), DFF, MT / 256, DM / 256, G, bx, wave, E);
.LBB0_866:
	s_or_b64 exec, exec, s[2:3]
	v_readlane_b32 s2, v254, 0
	v_readlane_b32 s3, v254, 1
	s_waitcnt lgkmcnt(0)
	v_mov_b32_e32 v0, v145
	s_barrier
	v_readlane_b32 s98, v254, 58
	s_lshr_b32 s98, s98, 3
	s_and_b32 s98, s98, 3
	s_mul_i32 s101, s98, 400
	s_cmp_eq_u32 s101, 0
	s_cbranch_scc1 STG5_skip
	s_memrealtime s[98:99]
	s_waitcnt lgkmcnt(0)
	s_mov_b32 s100, s98
STG5_spin:
	s_sleep 2
	s_memrealtime s[98:99]
	s_waitcnt lgkmcnt(0)
	s_sub_u32 s98, s98, s100
	s_cmp_lt_u32 s98, s101
	s_cbranch_scc1 STG5_spin
